# v41: v39 + non-temporal hint on the mix_rwkv output store
# baseline (speedup 1.0000x reference)
.LBB0_1395:
	s_waitcnt vmcnt(1)
	v_ashrrev_i32_e32 v26, 1, v4
	v_and_or_b32 v2, v7, 4, v5
	v_ashrrev_i32_e32 v27, 31, v26
	v_lshl_or_b32 v2, v2, 6, v6
	v_lshlrev_b64 v[22:23], 9, v[26:27]
	v_or_b32_e32 v22, v22, v2
	v_lshlrev_b32_e32 v9, 2, v2
	v_lshl_add_u64 v[28:29], v[22:23], 2, s[86:87]
	v_lshlrev_b64 v[22:23], 1, v[22:23]
	global_load_dwordx4 v[10:13], v9, s[16:17]
	global_load_dwordx4 v[14:17], v9, s[18:19]
	global_load_dwordx4 v[18:21], v9, s[20:21]
	v_lshl_add_u64 v[30:31], s[42:43], 0, v[22:23]
	v_lshl_add_u64 v[32:33], s[44:45], 0, v[22:23]
	v_lshl_add_u64 v[34:35], s[46:47], 0, v[22:23]
	v_lshl_add_u64 v[36:37], s[14:15], 0, v[22:23]
	global_load_dwordx4 v[22:25], v[28:29], off nt
	global_load_dwordx2 v[38:39], v[30:31], off nt
	global_load_dwordx2 v[40:41], v[32:33], off nt
	global_load_dwordx2 v[42:43], v[34:35], off nt
	global_load_dwordx2 v[44:45], v[36:37], off nt
	v_mad_i64_i32 v[26:27], s[10:11], v26, s2, v[0:1]
	v_lshlrev_b32_e32 v2, 1, v2
	v_lshl_add_u64 v[26:27], v[26:27], 0, v[2:3]
	v_add_u32_e32 v4, s4, v4
	v_cmp_lt_i32_e32 vcc, s3, v4
	s_or_b64 s[8:9], vcc, s[8:9]
	v_add_u32_e32 v7, s0, v7
	s_waitcnt vmcnt(4)
	v_add_f32_e32 v2, v22, v23
	v_add_f32_e32 v2, v2, v24
	s_waitcnt vmcnt(3)
	v_lshlrev_b32_e32 v28, 16, v38
	v_and_b32_e32 v29, 0xffff0000, v38
	s_waitcnt vmcnt(2)
	v_lshlrev_b32_e32 v32, 16, v40
	v_and_b32_e32 v33, 0xffff0000, v40
	v_add_f32_e32 v2, v2, v25
	v_lshlrev_b32_e32 v30, 16, v39
	v_and_b32_e32 v31, 0xffff0000, v39
	v_lshlrev_b32_e32 v34, 16, v41
	v_and_b32_e32 v35, 0xffff0000, v41
	v_pk_mul_f32 v[28:29], v[28:29], v[32:33]
	v_add_f32_dpp v2, v2, v2 quad_perm:[1,0,3,2] row_mask:0xf bank_mask:0xf bound_ctrl:1
	v_pk_mul_f32 v[30:31], v[30:31], v[34:35]
	v_pk_mul_f32 v[10:11], v[10:11], v[28:29]
	v_add_f32_dpp v2, v2, v2 quad_perm:[2,3,0,1] row_mask:0xf bank_mask:0xf bound_ctrl:1
	v_pk_mul_f32 v[12:13], v[12:13], v[30:31]
	v_add_f32_e32 v9, v10, v11
	v_add_f32_dpp v2, v2, v2 row_half_mirror row_mask:0xf bank_mask:0xf bound_ctrl:1
	v_add_f32_e32 v9, v9, v12
	v_add_f32_e32 v9, v13, v9
	v_add_f32_dpp v2, v2, v2 row_ror:8 row_mask:0xf bank_mask:0xf bound_ctrl:1
	v_mul_f32_e32 v2, 0x3c800000, v2
	v_add_f32_dpp v9, v9, v9 quad_perm:[1,0,3,2] row_mask:0xf bank_mask:0xf bound_ctrl:1
	v_pk_add_f32 v[10:11], v[22:23], v[2:3] op_sel_hi:[1,0] neg_lo:[0,1] neg_hi:[0,1]
	v_pk_add_f32 v[12:13], v[24:25], v[2:3] op_sel_hi:[1,0] neg_lo:[0,1] neg_hi:[0,1]
	v_add_f32_dpp v9, v9, v9 quad_perm:[2,3,0,1] row_mask:0xf bank_mask:0xf bound_ctrl:1
	v_pk_mul_f32 v[22:23], v[10:11], v[10:11]
	v_pk_mul_f32 v[24:25], v[12:13], v[12:13]
	v_add_f32_dpp v2, v9, v9 row_half_mirror row_mask:0xf bank_mask:0xf bound_ctrl:1
	v_add_f32_e32 v9, v22, v23
	v_add_f32_e32 v9, v24, v9
	v_add_f32_e32 v9, v25, v9
	s_waitcnt vmcnt(1)
	v_lshlrev_b32_e32 v36, 16, v42
	v_and_b32_e32 v37, 0xffff0000, v42
	v_add_f32_dpp v9, v9, v9 quad_perm:[1,0,3,2] row_mask:0xf bank_mask:0xf bound_ctrl:1
	v_lshlrev_b32_e32 v38, 16, v43
	v_and_b32_e32 v39, 0xffff0000, v43
	v_add_f32_dpp v9, v9, v9 quad_perm:[2,3,0,1] row_mask:0xf bank_mask:0xf bound_ctrl:1
	v_add_f32_dpp v2, v2, v2 row_ror:8 row_mask:0xf bank_mask:0xf bound_ctrl:1
	s_waitcnt vmcnt(0)
	v_lshlrev_b32_e32 v40, 16, v44
	v_add_f32_dpp v9, v9, v9 row_half_mirror row_mask:0xf bank_mask:0xf bound_ctrl:1
	v_and_b32_e32 v41, 0xffff0000, v44
	v_lshlrev_b32_e32 v42, 16, v45
	v_add_f32_dpp v9, v9, v9 row_ror:8 row_mask:0xf bank_mask:0xf bound_ctrl:1
	v_fmamk_f32 v9, v9, 0x3c800000, v8
	v_mul_f32_e32 v22, 0x4b800000, v9
	v_cmp_gt_f32_e32 vcc, s1, v9
	v_and_b32_e32 v43, 0xffff0000, v45
	s_nop 0
	v_cndmask_b32_e32 v9, v9, v22, vcc
	v_rsq_f32_e32 v9, v9
	s_nop 0
	v_mul_f32_e32 v22, 0x45800000, v9
	v_cndmask_b32_e32 v22, v9, v22, vcc
	v_pk_mul_f32 v[10:11], v[10:11], v[22:23] op_sel_hi:[1,0]
	v_pk_mul_f32 v[12:13], v[12:13], v[22:23] op_sel_hi:[1,0]
	v_pk_fma_f32 v[10:11], v[14:15], v[10:11], v[18:19]
	v_pk_fma_f32 v[12:13], v[16:17], v[12:13], v[20:21]
	v_pk_fma_f32 v[10:11], v[2:3], v[36:37], v[10:11] op_sel_hi:[0,1,1]
	v_pk_fma_f32 v[12:13], v[2:3], v[38:39], v[12:13] op_sel_hi:[0,1,1]
	v_pk_mul_f32 v[10:11], v[10:11], v[40:41]
	v_pk_mul_f32 v[12:13], v[12:13], v[42:43]
	v_cvt_pk_bf16_f32 v10, v10, v11
	v_cvt_pk_bf16_f32 v11, v12, v13
	global_store_dwordx2 v[26:27], v[10:11], off offset:1024 nt
	s_andn2_b64 exec, exec, s[8:9]
	s_cbranch_execnz .LBB0_1395
